# v33 plus: the 16 packed f32 FMAs of the attention softmax scaling split into scalar FMAs
# baseline (speedup 1.0000x reference)
; __device__ __forceinline__ void partialSM(f32x16& p0, f32x16& p1, float& m_reg, float& mn, float& alpha) {
;     ...
;   if (__builtin_expect(__all(pmax - m_reg <= THR / SCALE), 1)) { mn = m_reg; alpha = 1.f; }
;   else { mn = fmaxf(m_reg, pmax); alpha = __builtin_amdgcn_exp2f((m_reg - mn) * C); m_reg = mn; }
;   float mnC = -mn * C;
;   for (int r = 0; r < 16; ++r) p0[r] = fmaf(p0[r], C, mnC); for (int r = 0; r < 16; ++r) p1[r] = fmaf(p1[r], C, mnC);
;   for (int r = 0; r < 16; ++r) p0[r] = __builtin_amdgcn_exp2f(p0[r]);
; __device__ __forceinline__ void finishSM(f32x16& p0, f32x16& p1, float alpha, float& l_reg, bf16x8& pa0, bf16x8& pa1, bf16x8& pa2, bf16x8& pa3) {
;     ...
;   float ps = 0; for (int r = 0; r < 16; ++r) ps += p0[r]; for (int r = 0; r < 16; ++r) ps += p1[r];
;   { auto rr = __builtin_amdgcn_permlane32_swap(__float_as_uint(ps), __float_as_uint(ps), false, false);
;     ps = __uint_as_float(rr[0]) + __uint_as_float(rr[1]); }
;   l_reg = l_reg * alpha + ps;
.LBB0_482:
	v_cndmask_b32_e64 v166, v166, v2, s[6:7]
	v_mul_f32_e32 v2, 0xbe0293ee, v166
	v_fmamk_f32 v84, v84, 0x3e0293ee, v2
	v_fmamk_f32 v85, v85, 0x3e0293ee, v2
	v_fmamk_f32 v86, v86, 0x3e0293ee, v2
	v_fmamk_f32 v87, v87, 0x3e0293ee, v2
	v_fmamk_f32 v88, v88, 0x3e0293ee, v2
	v_fmamk_f32 v89, v89, 0x3e0293ee, v2
	v_fmamk_f32 v90, v90, 0x3e0293ee, v2
	v_fmamk_f32 v91, v91, 0x3e0293ee, v2
	v_fmamk_f32 v92, v92, 0x3e0293ee, v2
	v_fmamk_f32 v93, v93, 0x3e0293ee, v2
	v_fmamk_f32 v94, v94, 0x3e0293ee, v2
	v_fmamk_f32 v95, v95, 0x3e0293ee, v2
	v_fmamk_f32 v96, v96, 0x3e0293ee, v2
	v_fmamk_f32 v97, v97, 0x3e0293ee, v2
	v_fmamk_f32 v98, v98, 0x3e0293ee, v2
	v_fmamk_f32 v99, v99, 0x3e0293ee, v2
	v_exp_f32_e32 v216, v84
	v_exp_f32_e32 v218, v85
	v_exp_f32_e32 v214, v86
	v_exp_f32_e32 v217, v87
	v_exp_f32_e32 v213, v88
	v_exp_f32_e32 v215, v89
	v_exp_f32_e32 v211, v90
	v_exp_f32_e32 v212, v91
	v_exp_f32_e32 v208, v92
	v_exp_f32_e32 v210, v93
	v_exp_f32_e32 v207, v94
	v_exp_f32_e32 v209, v95
	v_exp_f32_e32 v204, v96
	v_exp_f32_e32 v206, v97
	v_exp_f32_e32 v203, v98
	v_exp_f32_e32 v205, v99
	v_add_f32_e32 v84, v200, v201
	v_fmac_f32_e32 v84, v198, v199
	v_add_f32_e32 v199, v219, v220
	s_add_i32 s16, s16, 2
	v_fmac_f32_e32 v199, v84, v202
	v_fma_f32 v162, v68, s22, v2
	v_fma_f32 v163, v69, s22, v2
	v_fma_f32 v160, v70, s22, v2
	v_fma_f32 v161, v71, s22, v2
	v_fma_f32 v158, v72, s22, v2
	v_fma_f32 v159, v73, s22, v2
	v_fma_f32 v156, v74, s22, v2
	v_fma_f32 v157, v75, s22, v2
	v_fma_f32 v154, v76, s22, v2
	v_fma_f32 v155, v77, s22, v2
	v_fma_f32 v152, v78, s22, v2
	v_fma_f32 v153, v79, s22, v2
	v_fma_f32 v150, v80, s22, v2
	v_fma_f32 v151, v81, s22, v2
	v_fma_f32 v148, v82, s22, v2
	v_fma_f32 v149, v83, s22, v2
	s_cmp_ge_u32 s91, s90
	s_waitcnt lgkmcnt(0)
	s_barrier
	s_cbranch_scc1 .LBB0_484
	v_mov_b32_e32 v198, v221
	s_branch .LBB0_474

; __device__ __forceinline__ void partialSM(f32x16& p0, f32x16& p1, float& m_reg, float& mn, float& alpha) {
;     ...
;   if (__builtin_expect(__all(pmax - m_reg <= THR / SCALE), 1)) { mn = m_reg; alpha = 1.f; }
;   else { mn = fmaxf(m_reg, pmax); alpha = __builtin_amdgcn_exp2f((m_reg - mn) * C); m_reg = mn; }
;   float mnC = -mn * C;
;   for (int r = 0; r < 16; ++r) p0[r] = fmaf(p0[r], C, mnC); for (int r = 0; r < 16; ++r) p1[r] = fmaf(p1[r], C, mnC);
;   for (int r = 0; r < 16; ++r) p0[r] = __builtin_amdgcn_exp2f(p0[r]);
.Lstg_r2:
	v_cndmask_b32_e64 v166, v166, v2, s[6:7]
	v_mul_f32_e32 v2, 0xbe0293ee, v166
	v_fmamk_f32 v84, v84, 0x3e0293ee, v2
	v_fmamk_f32 v85, v85, 0x3e0293ee, v2
	v_fmamk_f32 v86, v86, 0x3e0293ee, v2
	v_fmamk_f32 v87, v87, 0x3e0293ee, v2
	v_fmamk_f32 v88, v88, 0x3e0293ee, v2
	v_fmamk_f32 v89, v89, 0x3e0293ee, v2
	v_fmamk_f32 v90, v90, 0x3e0293ee, v2
	v_fmamk_f32 v91, v91, 0x3e0293ee, v2
	v_fmamk_f32 v92, v92, 0x3e0293ee, v2
	v_fmamk_f32 v93, v93, 0x3e0293ee, v2
	v_fmamk_f32 v94, v94, 0x3e0293ee, v2
	v_fmamk_f32 v95, v95, 0x3e0293ee, v2
	v_fmamk_f32 v96, v96, 0x3e0293ee, v2
	v_fmamk_f32 v97, v97, 0x3e0293ee, v2
	v_fmamk_f32 v98, v98, 0x3e0293ee, v2
	v_fmamk_f32 v99, v99, 0x3e0293ee, v2
	v_exp_f32_e32 v216, v84
	v_exp_f32_e32 v218, v85
	v_exp_f32_e32 v214, v86
	v_exp_f32_e32 v217, v87
	v_exp_f32_e32 v213, v88
	v_exp_f32_e32 v215, v89
	v_exp_f32_e32 v211, v90
	v_exp_f32_e32 v212, v91
	v_exp_f32_e32 v208, v92
	v_exp_f32_e32 v210, v93
	v_exp_f32_e32 v207, v94
	v_exp_f32_e32 v209, v95
	v_exp_f32_e32 v204, v96
	v_exp_f32_e32 v206, v97
	v_exp_f32_e32 v203, v98
	v_exp_f32_e32 v205, v99
	v_add_f32_e32 v84, v200, v201
	v_fmac_f32_e32 v84, v198, v199
	v_add_f32_e32 v199, v219, v220
	s_add_i32 s16, s16, 2
	v_fmac_f32_e32 v199, v84, v202
	v_fma_f32 v162, v68, s22, v2
	v_fma_f32 v163, v69, s22, v2
	v_fma_f32 v160, v70, s22, v2
	v_fma_f32 v161, v71, s22, v2
	v_fma_f32 v158, v72, s22, v2
	v_fma_f32 v159, v73, s22, v2
	v_fma_f32 v156, v74, s22, v2
	v_fma_f32 v157, v75, s22, v2
	v_fma_f32 v154, v76, s22, v2
	v_fma_f32 v155, v77, s22, v2
	v_fma_f32 v152, v78, s22, v2
	v_fma_f32 v153, v79, s22, v2
	v_fma_f32 v150, v80, s22, v2
	v_fma_f32 v151, v81, s22, v2
	v_fma_f32 v148, v82, s22, v2
	v_fma_f32 v149, v83, s22, v2
	s_cmp_ge_u32 s91, s90
	s_cbranch_scc1 .LBB0_484
	v_mov_b32_e32 v198, v221
	s_branch .Lstg_loop
